# attention latent loop: loop edge rotated - next tile's K/V address arithmetic and loads issued in front of the rendezvous barrier instead of behind it
# speedup vs baseline: 1.0046x; 1.0046x over previous
; __device__ __forceinline__ void attn_unit(const TI ti, CArgs& a, int b, int hd, int qrow0, int st_lo, int st_hi, float mfix, float lam, float lam_init, const float* subg, unsigned char* ldsg) {
;     ...
;     ATT_LOAD(st_lo); ATT_STORE(0);
;     __syncthreads();
;     for (int st = st_lo; st < st_hi; ++st) {
;         const int bi = (st - st_lo) & 1;
;         if (st + 1 < st_hi) ATT_LOAD(st + 1);
;     ...
;         if (st + 1 < st_hi) ATT_STORE(bi ^ 1);
;         __syncthreads();
.LBB0_351:
	s_or_b64 exec, exec, s[4:5]
	s_add_i32 s17, s17, 1
	s_setprio 0
	s_xor_b32 s4, s48, 1
	s_mul_i32 s4, s4, 0x8c00
	s_add_i32 s4, s4, 0
	v_add_u32_e32 v82, s4, v147
	v_add_u32_e32 v83, v82, v155
	v_add_u32_e32 v82, v82, v156
	s_add_i32 s37, s37, 64
	s_add_i32 s39, s39, 64
	s_waitcnt vmcnt(3)
	ds_write_b128 v83, v[122:125]
	s_waitcnt vmcnt(2)
	ds_write_b128 v82, v[126:129]
	v_add3_u32 v82, s4, v157, v158
	s_cmp_eq_u32 s17, 35
	s_waitcnt vmcnt(1)
	ds_write_b16 v82, v118 offset:17408
	ds_write_b16_d16_hi v82, v118 offset:17552
	s_waitcnt vmcnt(0)
	ds_write_b16 v82, v114 offset:18560
	ds_write_b16_d16_hi v82, v114 offset:18704
	ds_write_b16 v82, v119 offset:17696
	ds_write_b16_d16_hi v82, v119 offset:17840
	ds_write_b16 v82, v115 offset:18848
	ds_write_b16_d16_hi v82, v115 offset:18992
	ds_write_b16 v82, v120 offset:17984
	ds_write_b16_d16_hi v82, v120 offset:18128
	ds_write_b16 v82, v116 offset:19136
	ds_write_b16_d16_hi v82, v116 offset:19280
	ds_write_b16 v82, v121 offset:18272
	ds_write_b16_d16_hi v82, v121 offset:18416
	ds_write_b16 v82, v117 offset:19424
	ds_write_b16_d16_hi v82, v117 offset:19568
	s_waitcnt lgkmcnt(0)
	s_cmp_eq_u32 s17, 35
	s_cbranch_scc1 .Lattn_last
	s_cmp_lt_u32 s17, 31
	s_cselect_b32 s4, s39, s37
	s_ashr_i32 s5, s4, 31
	s_lshl_b64 s[4:5], s[4:5], 11
	s_add_u32 s33, s27, s4
	s_addc_u32 s36, s34, s5
	v_mov_b32_e32 v82, s33
	v_mov_b32_e32 v83, s36
	s_add_u32 s4, s18, s4
	s_addc_u32 s5, s35, s5
	v_lshl_add_u64 v[82:83], v[140:141], 1, v[82:83]
	v_mov_b32_e32 v84, s4
	v_mov_b32_e32 v85, s5
	v_add_co_u32_e32 v86, vcc, s79, v82
	s_nop 0
	v_addc_co_u32_e32 v87, vcc, 0, v83, vcc
	global_load_dwordx4 v[122:125], v[82:83], off
	global_load_dwordx4 v[126:129], v[86:87], off
	v_lshl_add_u64 v[82:83], v[142:143], 1, v[84:85]
	global_load_dwordx4 v[118:121], v[82:83], off
	global_load_dwordx4 v[114:117], v[82:83], off offset:16
	s_barrier
	s_branch .Lattn_body
.Lattn_last:
	s_barrier
	s_branch .LBB0_356
.LBB0_352:
	s_cmp_lt_u32 s17, 31
	s_cselect_b32 s4, s39, s37
	s_ashr_i32 s5, s4, 31
	s_lshl_b64 s[4:5], s[4:5], 11
	s_add_u32 s33, s27, s4
	s_addc_u32 s36, s34, s5
	v_mov_b32_e32 v82, s33
	v_mov_b32_e32 v83, s36
	s_add_u32 s4, s18, s4
	s_addc_u32 s5, s35, s5
	v_lshl_add_u64 v[82:83], v[140:141], 1, v[82:83]
	v_mov_b32_e32 v84, s4
	v_mov_b32_e32 v85, s5
	v_add_co_u32_e32 v86, vcc, s79, v82
	s_nop 0
	v_addc_co_u32_e32 v87, vcc, 0, v83, vcc
	global_load_dwordx4 v[122:125], v[82:83], off
	global_load_dwordx4 v[126:129], v[86:87], off
	v_lshl_add_u64 v[82:83], v[142:143], 1, v[84:85]
	global_load_dwordx4 v[118:121], v[82:83], off
	global_load_dwordx4 v[114:117], v[82:83], off offset:16
; #define LAS __attribute__((address_space(3)))
; #define ATT_QK(SX, sub) do { __builtin_amdgcn_s_setprio(1); _Pragma("unroll") for (int ks = 0; ks < 4; ++ks) { \
;             const bf16x8 kf = *(LAS const bf16x8*)(Bb + KOFF + ((sub) * 32 + r) * 272 + (c * 64 + 16 * ks + 8 * h) * 2); SX = MFMA32(kf, qf[ks], SX); } __builtin_amdgcn_s_setprio(0); } while (0)
; #define ATT_SOFT(SX, P0, P1) do { float p[16]; _Pragma("unroll") for (int i = 0; i < 16; ++i) { p[i] = __builtin_amdgcn_exp2f(SX[i]); lsum += p[i]; } \
;             P0 = pk8f(p[0], p[1], p[2], p[3], p[4], p[5], p[6], p[7]); P1 = pk8f(p[8], p[9], p[10], p[11], p[12], p[13], p[14], p[15]); } while (0)
; #define ATT_PV(sub, P0, P1) do { __builtin_amdgcn_s_setprio(1); _Pragma("unroll") for (int et = 0; et < 4; ++et) { _Pragma("unroll") for (int s = 0; s < 2; ++s) { \
;             const bf16x8 vf = *(LAS const bf16x8*)(Bb + VOFF + (et * 32 + r) * 144 + ((sub) * 32 + 16 * s + 8 * h) * 2); O[et] = MFMA32(vf, s ? P1 : P0, O[et]); } } __builtin_amdgcn_s_setprio(0); } while (0)
; __device__ __forceinline__ void attn_unit(const TI ti, CArgs& a, int b, int hd, int qrow0, int st_lo, int st_hi, float mfix, float lam, float lam_init, const float* subg, unsigned char* ldsg) {
;     ...
;         LAS const unsigned char* Bb = L + bi * BUFB;
;         f32x16 Sx0, Sx1; bf16x8 pa0, pa1, pc0, pc1;
; #pragma unroll
;         for (int i = 0; i < 16; ++i) { Sx0[i] = -mfix; Sx1[i] = -mfix; }
;     ...
;         if (w < 4) {
;             ATT_QK(Sx0, 0); ATT_QK(Sx1, 1);
;             __builtin_amdgcn_sched_barrier(0);
;             ATT_SOFT(Sx0, pa0, pa1); ATT_PV(0, pa0, pa1);
;             ATT_SOFT(Sx1, pc0, pc1); ATT_PV(1, pc0, pc1);
.Lattn_body:
	s_and_b32 s48, s17, 1
	s_mul_i32 s4, s48, 0x8c00
	s_add_i32 s4, s4, 0
	s_setprio 1
	v_add_u32_e32 v82, s4, v160
	v_add_u32_e32 v151, v82, v161
	ds_read_b128 v[130:133], v151
	v_add3_u32 v150, s4, v144, v162
	s_and_saveexec_b64 s[4:5], s[40:41]
	s_xor_b64 s[4:5], exec, s[4:5]
	s_cbranch_execz .LBB0_354
	ds_read_b128 v[182:185], v151 offset:32
	ds_read_b128 v[198:201], v151 offset:64
	ds_read_b128 v[202:205], v151 offset:96
	ds_read_b128 v[206:209], v151 offset:8704
	ds_read_b128 v[210:213], v151 offset:8736
	ds_read_b128 v[236:239], v151 offset:8768
	ds_read_b128 v[240:243], v151 offset:8800
	s_setprio 1
	s_waitcnt lgkmcnt(7)
	v_mfma_f32_32x32x16_bf16 v[82:97], v[130:133], v[110:113], v[2:17]
	s_waitcnt lgkmcnt(6)
	v_mfma_f32_32x32x16_bf16 v[82:97], v[182:185], v[106:109], v[82:97]
	s_waitcnt lgkmcnt(5)
	v_mfma_f32_32x32x16_bf16 v[82:97], v[198:201], v[102:105], v[82:97]
	s_waitcnt lgkmcnt(4)
	v_mfma_f32_32x32x16_bf16 v[82:97], v[202:205], v[98:101], v[82:97]
	ds_read_b128 v[130:133], v150 offset:17408
	ds_read_b128 v[182:185], v150 offset:17440
	ds_read_b128 v[198:201], v150 offset:22016
	ds_read_b128 v[202:205], v150 offset:22048
	s_waitcnt lgkmcnt(7)
	v_mfma_f32_32x32x16_bf16 v[220:235], v[206:209], v[110:113], v[2:17]
	s_waitcnt lgkmcnt(6)
	v_mfma_f32_32x32x16_bf16 v[220:235], v[210:213], v[106:109], v[220:235]
	s_waitcnt lgkmcnt(5)
	v_mfma_f32_32x32x16_bf16 v[220:235], v[236:239], v[102:105], v[220:235]
	s_waitcnt lgkmcnt(4)
	v_mfma_f32_32x32x16_bf16 v[220:235], v[240:243], v[98:101], v[220:235]
	ds_read_b128 v[206:209], v150 offset:26624
	ds_read_b128 v[210:213], v150 offset:26656
	ds_read_b128 v[236:239], v150 offset:31232
	ds_read_b128 v[240:243], v150 offset:31264
	s_setprio 0
	v_exp_f32_e32 v169, v82
	v_exp_f32_e32 v170, v83
	v_exp_f32_e32 v171, v84
	v_exp_f32_e32 v174, v85
	v_exp_f32_e32 v175, v86
	v_exp_f32_e32 v176, v87
	v_exp_f32_e32 v177, v88
	v_exp_f32_e32 v179, v89
	v_exp_f32_e32 v90, v90
	v_exp_f32_e32 v91, v91
	v_exp_f32_e32 v92, v92
	v_exp_f32_e32 v93, v93
	v_exp_f32_e32 v94, v94
	v_exp_f32_e32 v95, v95
	v_exp_f32_e32 v96, v96
	v_exp_f32_e32 v97, v97
	v_cvt_pk_bf16_f32 v82, v169, v170
	v_cvt_pk_bf16_f32 v83, v171, v174
	v_cvt_pk_bf16_f32 v84, v175, v176
	v_cvt_pk_bf16_f32 v85, v177, v179
	v_cvt_pk_bf16_f32 v86, v90, v91
	v_cvt_pk_bf16_f32 v87, v92, v93
	v_cvt_pk_bf16_f32 v88, v94, v95
	v_cvt_pk_bf16_f32 v89, v96, v97
	s_setprio 1
	s_waitcnt lgkmcnt(7)
	v_mfma_f32_32x32x16_bf16 v[18:33], v[130:133], v[82:85], v[18:33]
	v_add_f32_e32 v0, v169, v0
	v_add_f32_e32 v0, v170, v0
	s_waitcnt lgkmcnt(6)
	v_mfma_f32_32x32x16_bf16 v[18:33], v[182:185], v[86:89], v[18:33]
	v_add_f32_e32 v0, v171, v0
	v_add_f32_e32 v0, v174, v0
	ds_read_b128 v[130:133], v150 offset:17472
	ds_read_b128 v[182:185], v150 offset:17504
	s_waitcnt lgkmcnt(7)
	v_mfma_f32_32x32x16_bf16 v[34:49], v[198:201], v[82:85], v[34:49]
	v_add_f32_e32 v0, v175, v0
	v_add_f32_e32 v0, v176, v0
	s_waitcnt lgkmcnt(6)
	v_mfma_f32_32x32x16_bf16 v[34:49], v[202:205], v[86:89], v[34:49]
	v_add_f32_e32 v0, v177, v0
	v_add_f32_e32 v0, v179, v0
	ds_read_b128 v[198:201], v150 offset:22080
	ds_read_b128 v[202:205], v150 offset:22112
	s_waitcnt lgkmcnt(7)
	v_mfma_f32_32x32x16_bf16 v[66:81], v[206:209], v[82:85], v[66:81]
	v_add_f32_e32 v0, v90, v0
	v_add_f32_e32 v0, v91, v0
	s_waitcnt lgkmcnt(6)
	v_mfma_f32_32x32x16_bf16 v[66:81], v[210:213], v[86:89], v[66:81]
	v_add_f32_e32 v0, v92, v0
	v_add_f32_e32 v0, v93, v0
	ds_read_b128 v[206:209], v150 offset:26688
	ds_read_b128 v[210:213], v150 offset:26720
	s_waitcnt lgkmcnt(7)
	v_mfma_f32_32x32x16_bf16 v[50:65], v[236:239], v[82:85], v[50:65]
	v_add_f32_e32 v0, v94, v0
	v_add_f32_e32 v0, v95, v0
	s_waitcnt lgkmcnt(6)
	v_mfma_f32_32x32x16_bf16 v[50:65], v[240:243], v[86:89], v[50:65]
	v_add_f32_e32 v0, v96, v0
	v_add_f32_e32 v0, v97, v0
	ds_read_b128 v[236:239], v150 offset:31296
	ds_read_b128 v[240:243], v150 offset:31328
	s_setprio 0
	v_exp_f32_e32 v181, v220
	v_exp_f32_e32 v197, v221
	v_exp_f32_e32 v214, v222
	v_exp_f32_e32 v244, v223
	v_exp_f32_e32 v245, v224
	v_exp_f32_e32 v246, v225
	v_exp_f32_e32 v247, v226
	v_exp_f32_e32 v248, v227
	v_exp_f32_e32 v228, v228
	v_exp_f32_e32 v229, v229
	v_exp_f32_e32 v230, v230
	v_exp_f32_e32 v231, v231
	v_exp_f32_e32 v232, v232
	v_exp_f32_e32 v233, v233
	v_exp_f32_e32 v234, v234
	v_exp_f32_e32 v235, v235
	v_cvt_pk_bf16_f32 v220, v181, v197
	v_cvt_pk_bf16_f32 v221, v214, v244
	v_cvt_pk_bf16_f32 v222, v245, v246
	v_cvt_pk_bf16_f32 v223, v247, v248
	v_cvt_pk_bf16_f32 v224, v228, v229
	v_cvt_pk_bf16_f32 v225, v230, v231
	v_cvt_pk_bf16_f32 v226, v232, v233
	v_cvt_pk_bf16_f32 v227, v234, v235
	s_setprio 1
	s_waitcnt lgkmcnt(7)
	v_mfma_f32_32x32x16_bf16 v[18:33], v[130:133], v[220:223], v[18:33]
	v_add_f32_e32 v0, v181, v0
	v_add_f32_e32 v0, v197, v0
	s_waitcnt lgkmcnt(6)
	v_mfma_f32_32x32x16_bf16 v[18:33], v[182:185], v[224:227], v[18:33]
	v_add_f32_e32 v0, v214, v0
	v_add_f32_e32 v0, v244, v0
	s_waitcnt lgkmcnt(5)
	v_mfma_f32_32x32x16_bf16 v[34:49], v[198:201], v[220:223], v[34:49]
	v_add_f32_e32 v0, v245, v0
	v_add_f32_e32 v0, v246, v0
	s_waitcnt lgkmcnt(4)
	v_mfma_f32_32x32x16_bf16 v[34:49], v[202:205], v[224:227], v[34:49]
	v_add_f32_e32 v0, v247, v0
	v_add_f32_e32 v0, v248, v0
	s_waitcnt lgkmcnt(3)
	v_mfma_f32_32x32x16_bf16 v[66:81], v[206:209], v[220:223], v[66:81]
	v_add_f32_e32 v0, v228, v0
	v_add_f32_e32 v0, v229, v0
	s_waitcnt lgkmcnt(2)
	v_mfma_f32_32x32x16_bf16 v[66:81], v[210:213], v[224:227], v[66:81]
	v_add_f32_e32 v0, v230, v0
	v_add_f32_e32 v0, v231, v0
	s_waitcnt lgkmcnt(1)
	v_mfma_f32_32x32x16_bf16 v[50:65], v[236:239], v[220:223], v[50:65]
	v_add_f32_e32 v0, v232, v0
	v_add_f32_e32 v0, v233, v0
	s_waitcnt lgkmcnt(0)
	v_mfma_f32_32x32x16_bf16 v[50:65], v[240:243], v[224:227], v[50:65]
	v_add_f32_e32 v0, v234, v0
	v_add_f32_e32 v0, v235, v0
